# xcd_barrier_complete: 16 per-XCD counter loads issued back to back (one wait per poll round instead of 16 serialized sc1 round trips)
# baseline (speedup 1.0000x reference)
; __device__ __forceinline__ unsigned xb_ld(unsigned* p)              { return __hip_atomic_load(p, __ATOMIC_RELAXED, __HIP_MEMORY_SCOPE_AGENT); }
; __device__ __forceinline__ void xcd_barrier_complete(unsigned* bar, unsigned x, unsigned& nloc, unsigned& nx) {
;     ...
;     for (;;) {
;         sum = 0u; cnt = 0u; mine = 0u;
; #pragma unroll
;         for (unsigned j = 0; j < 16; ++j) { const unsigned c = xb_ld(&bar[XB_XCNT(j)]); sum += c; cnt += (c > 0u) ? 1u : 0u; mine = (j == x) ? c : mine; }
;         if (sum == G) break;
;         __builtin_amdgcn_s_sleep(1);
;         if ((++sp & 255u) == 0u) { if (xb_ld(&bar[XB_TMO])) break; if (sp > XB_SPIN_CAP) { atomicAdd(&bar[XB_TMO], 1u); break; } }
;     }
.LBB0_398:
	v_readlane_b32 s4, v252, 25
	v_readlane_b32 s5, v252, 26
	v_readlane_b32 s3, v253, 49
	s_mov_b64 s[6:7], -1
	s_nop 2
	global_load_dword v0, v1, s[4:5] sc1
	v_readlane_b32 s4, v252, 27
	v_readlane_b32 s5, v252, 28
	s_waitcnt lgkmcnt(0)
	s_nop 3
	global_load_dword v2, v1, s[4:5] sc1
	v_readlane_b32 s4, v252, 29
	v_readlane_b32 s5, v252, 30
	s_nop 4
	global_load_dword v3, v1, s[4:5] sc1
	v_readlane_b32 s4, v252, 31
	v_readlane_b32 s5, v252, 32
	s_nop 4
	global_load_dword v4, v1, s[4:5] sc1
	v_readlane_b32 s4, v252, 33
	v_readlane_b32 s5, v252, 34
	s_nop 4
	global_load_dword v5, v1, s[4:5] sc1
	v_readlane_b32 s4, v252, 35
	v_readlane_b32 s5, v252, 36
	s_nop 4
	global_load_dword v6, v1, s[4:5] sc1
	v_readlane_b32 s4, v252, 37
	v_readlane_b32 s5, v252, 38
	s_nop 4
	global_load_dword v7, v1, s[4:5] sc1
	v_readlane_b32 s4, v252, 39
	v_readlane_b32 s5, v252, 40
	s_nop 4
	global_load_dword v8, v1, s[4:5] sc1
	v_readlane_b32 s4, v252, 41
	v_readlane_b32 s5, v252, 42
	s_nop 4
	global_load_dword v9, v1, s[4:5] sc1
	v_readlane_b32 s4, v252, 43
	v_readlane_b32 s5, v252, 44
	s_nop 4
	global_load_dword v10, v1, s[4:5] sc1
	v_readlane_b32 s4, v252, 45
	v_readlane_b32 s5, v252, 46
	s_nop 4
	global_load_dword v11, v1, s[4:5] sc1
	v_readlane_b32 s4, v252, 47
	v_readlane_b32 s5, v252, 48
	s_nop 4
	global_load_dword v12, v1, s[4:5] sc1
	v_readlane_b32 s4, v252, 49
	v_readlane_b32 s5, v252, 50
	s_nop 4
	global_load_dword v13, v1, s[4:5] sc1
	v_readlane_b32 s4, v252, 51
	v_readlane_b32 s5, v252, 52
	s_nop 4
	global_load_dword v14, v1, s[4:5] sc1
	v_readlane_b32 s4, v252, 53
	v_readlane_b32 s5, v252, 54
	s_nop 4
	global_load_dword v15, v1, s[4:5] sc1
	v_readlane_b32 s4, v252, 55
	v_readlane_b32 s5, v252, 56
	s_nop 4
	global_load_dword v16, v1, s[4:5] sc1
	s_mov_b64 s[4:5], -1
	s_waitcnt vmcnt(0)
	v_add_u32_e32 v17, v2, v0
	v_add_u32_e32 v17, v17, v3
	v_add_u32_e32 v17, v17, v4
	v_add_u32_e32 v17, v17, v5
	v_add_u32_e32 v17, v17, v6
	v_add_u32_e32 v17, v17, v7
	v_add_u32_e32 v17, v17, v8
	v_add_u32_e32 v17, v17, v9
	v_add_u32_e32 v17, v17, v10
	v_add_u32_e32 v17, v17, v11
	v_add_u32_e32 v17, v17, v12
	v_add_u32_e32 v17, v17, v13
	v_add_u32_e32 v17, v17, v14
	v_add_u32_e32 v17, v17, v15
	v_add_u32_e32 v17, v17, v16
	v_cmp_eq_u32_e32 vcc, s3, v17
	s_cbranch_vccnz .LBB0_397
	s_and_b32 s3, s2, 0xff
	s_cmp_eq_u32 s3, 0
	s_mov_b64 s[8:9], -1
	s_sleep 1
	s_cbranch_scc0 .LBB0_402
	v_readlane_b32 s4, v252, 23
	v_readlane_b32 s5, v252, 24
	s_nop 4
	global_load_dword v17, v1, s[4:5] sc1
	s_waitcnt vmcnt(0)
	v_cmp_eq_u32_e32 vcc, 0, v17
	s_cbranch_vccnz .LBB0_404
	s_mov_b64 s[8:9], 0
	s_mov_b64 s[4:5], -1
